# phase 0 adaLN GEMV: 16 strided row loads in flight per batch (two value sets) instead of 8
# speedup vs baseline: 1.0048x; 1.0048x over previous
.LBB0_98:
	v_lshl_add_u64 v[36:37], v[2:3], 0, s[10:11]
	v_add_co_u32_e32 v38, vcc, s53, v36
	s_mov_b32 s9, 0xc000
	s_nop 0
	v_addc_co_u32_e32 v39, vcc, 0, v37, vcc
	v_add_co_u32_e32 v40, vcc, s9, v36
	s_mov_b32 s9, 0x12000
	s_nop 0
	v_addc_co_u32_e32 v41, vcc, 0, v37, vcc
	v_add_co_u32_e32 v42, vcc, s9, v36
	s_mov_b32 s9, 0x18000
	s_nop 0
	v_addc_co_u32_e32 v43, vcc, 0, v37, vcc
	global_load_dword v60, v[36:37], off
	v_add_co_u32_e32 v44, vcc, s9, v36
	s_mov_b32 s9, 0x1e000
	s_nop 0
	v_addc_co_u32_e32 v45, vcc, 0, v37, vcc
	v_add_co_u32_e32 v46, vcc, s9, v36
	s_mov_b32 s9, 0x24000
	s_nop 0
	v_addc_co_u32_e32 v47, vcc, 0, v37, vcc
	v_add_co_u32_e32 v48, vcc, s9, v36
	s_mov_b32 s9, 0x2a000
	s_nop 0
	v_addc_co_u32_e32 v49, vcc, 0, v37, vcc
	v_add_co_u32_e32 v36, vcc, s9, v36
	s_add_u32 s10, s10, 0x30000
	s_nop 0
	v_addc_co_u32_e32 v37, vcc, 0, v37, vcc
	global_load_dword v62, v[38:39], off
	global_load_dword v64, v[40:41], off
	global_load_dword v66, v[42:43], off
	global_load_dword v68, v[44:45], off
	global_load_dword v70, v[46:47], off
	global_load_dword v72, v[48:49], off
	global_load_dword v74, v[36:37], off
	v_lshl_add_u64 v[36:37], v[2:3], 0, s[10:11]
	v_add_co_u32_e32 v38, vcc, s53, v36
	s_mov_b32 s9, 0xc000
	s_nop 0
	v_addc_co_u32_e32 v39, vcc, 0, v37, vcc
	v_add_co_u32_e32 v40, vcc, s9, v36
	s_mov_b32 s9, 0x12000
	s_nop 0
	v_addc_co_u32_e32 v41, vcc, 0, v37, vcc
	v_add_co_u32_e32 v42, vcc, s9, v36
	s_mov_b32 s9, 0x18000
	s_nop 0
	v_addc_co_u32_e32 v43, vcc, 0, v37, vcc
	global_load_dword v78, v[36:37], off
	v_add_co_u32_e32 v44, vcc, s9, v36
	s_mov_b32 s9, 0x1e000
	s_nop 0
	v_addc_co_u32_e32 v45, vcc, 0, v37, vcc
	v_add_co_u32_e32 v46, vcc, s9, v36
	s_mov_b32 s9, 0x24000
	s_nop 0
	v_addc_co_u32_e32 v47, vcc, 0, v37, vcc
	v_add_co_u32_e32 v48, vcc, s9, v36
	s_mov_b32 s9, 0x2a000
	s_nop 0
	v_addc_co_u32_e32 v49, vcc, 0, v37, vcc
	v_add_co_u32_e32 v36, vcc, s9, v36
	s_add_u32 s10, s10, 0x30000
	s_nop 0
	v_addc_co_u32_e32 v37, vcc, 0, v37, vcc
	global_load_dword v80, v[38:39], off
	global_load_dword v82, v[40:41], off
	global_load_dword v84, v[42:43], off
	global_load_dword v86, v[44:45], off
	global_load_dword v88, v[46:47], off
	global_load_dword v90, v[48:49], off
	global_load_dword v92, v[36:37], off
	ds_read_b128 v[36:39], v34
	ds_read_b128 v[40:43], v34 offset:16
	ds_read_b128 v[44:47], v34 offset:4096
	ds_read_b128 v[48:51], v34 offset:4112
	ds_read_b128 v[52:55], v34 offset:8192
	ds_read_b128 v[56:59], v34 offset:8208
	s_waitcnt lgkmcnt(5)
	v_mov_b32_e32 v76, v36
	s_waitcnt lgkmcnt(3)
	v_mov_b32_e32 v77, v44
	v_mov_b32_e32 v44, v37
	v_mov_b32_e32 v36, v38
	v_mov_b32_e32 v37, v46
	v_mov_b32_e32 v46, v39
	v_mov_b32_e32 v38, v40
	s_waitcnt lgkmcnt(2)
	v_mov_b32_e32 v39, v48
	v_mov_b32_e32 v48, v41
	v_mov_b32_e32 v40, v42
	v_mov_b32_e32 v41, v50
	v_mov_b32_e32 v50, v43
	v_add_u32_e32 v34, 32, v34
	s_waitcnt vmcnt(15)
	v_pk_fma_f32 v[4:5], v[76:77], v[60:61], v[4:5] op_sel_hi:[1,0,1]
	s_waitcnt lgkmcnt(1)
	v_fmac_f32_e32 v18, v52, v60
	s_waitcnt vmcnt(14)
	v_pk_fma_f32 v[4:5], v[44:45], v[62:63], v[4:5] op_sel_hi:[1,0,1]
	v_fmac_f32_e32 v18, v53, v62
	s_waitcnt vmcnt(13)
	v_pk_fma_f32 v[4:5], v[36:37], v[64:65], v[4:5] op_sel_hi:[1,0,1]
	v_fmac_f32_e32 v18, v54, v64
	s_waitcnt vmcnt(12)
	v_pk_fma_f32 v[4:5], v[46:47], v[66:67], v[4:5] op_sel_hi:[1,0,1]
	v_fmac_f32_e32 v18, v55, v66
	s_waitcnt vmcnt(11)
	v_pk_fma_f32 v[4:5], v[38:39], v[68:69], v[4:5] op_sel_hi:[1,0,1]
	s_waitcnt lgkmcnt(0)
	v_fmac_f32_e32 v18, v56, v68
	s_waitcnt vmcnt(10)
	v_pk_fma_f32 v[4:5], v[48:49], v[70:71], v[4:5] op_sel_hi:[1,0,1]
	v_fmac_f32_e32 v18, v57, v70
	s_waitcnt vmcnt(9)
	v_pk_fma_f32 v[4:5], v[40:41], v[72:73], v[4:5] op_sel_hi:[1,0,1]
	v_fmac_f32_e32 v18, v58, v72
	s_waitcnt vmcnt(8)
	v_pk_fma_f32 v[4:5], v[50:51], v[74:75], v[4:5] op_sel_hi:[1,0,1]
	v_fmac_f32_e32 v18, v59, v74
	ds_read_b128 v[36:39], v34
	ds_read_b128 v[40:43], v34 offset:16
	ds_read_b128 v[44:47], v34 offset:4096
	ds_read_b128 v[48:51], v34 offset:4112
	ds_read_b128 v[52:55], v34 offset:8192
	ds_read_b128 v[56:59], v34 offset:8208
	s_waitcnt lgkmcnt(5)
	v_mov_b32_e32 v76, v36
	s_waitcnt lgkmcnt(3)
	v_mov_b32_e32 v77, v44
	v_mov_b32_e32 v44, v37
	v_mov_b32_e32 v36, v38
	v_mov_b32_e32 v37, v46
	v_mov_b32_e32 v46, v39
	v_mov_b32_e32 v38, v40
	s_waitcnt lgkmcnt(2)
	v_mov_b32_e32 v39, v48
	v_mov_b32_e32 v48, v41
	v_mov_b32_e32 v40, v42
	v_mov_b32_e32 v41, v50
	v_mov_b32_e32 v50, v43
	v_add_u32_e32 v34, 32, v34
	s_cmp_eq_u32 s10, 0x300000
	s_waitcnt vmcnt(7)
	v_pk_fma_f32 v[4:5], v[76:77], v[78:79], v[4:5] op_sel_hi:[1,0,1]
	s_waitcnt lgkmcnt(1)
	v_fmac_f32_e32 v18, v52, v78
	s_waitcnt vmcnt(6)
	v_pk_fma_f32 v[4:5], v[44:45], v[80:81], v[4:5] op_sel_hi:[1,0,1]
	v_fmac_f32_e32 v18, v53, v80
	s_waitcnt vmcnt(5)
	v_pk_fma_f32 v[4:5], v[36:37], v[82:83], v[4:5] op_sel_hi:[1,0,1]
	v_fmac_f32_e32 v18, v54, v82
	s_waitcnt vmcnt(4)
	v_pk_fma_f32 v[4:5], v[46:47], v[84:85], v[4:5] op_sel_hi:[1,0,1]
	v_fmac_f32_e32 v18, v55, v84
	s_waitcnt vmcnt(3)
	v_pk_fma_f32 v[4:5], v[38:39], v[86:87], v[4:5] op_sel_hi:[1,0,1]
	s_waitcnt lgkmcnt(0)
	v_fmac_f32_e32 v18, v56, v86
	s_waitcnt vmcnt(2)
	v_pk_fma_f32 v[4:5], v[48:49], v[88:89], v[4:5] op_sel_hi:[1,0,1]
	v_fmac_f32_e32 v18, v57, v88
	s_waitcnt vmcnt(1)
	v_pk_fma_f32 v[4:5], v[40:41], v[90:91], v[4:5] op_sel_hi:[1,0,1]
	v_fmac_f32_e32 v18, v58, v90
	s_waitcnt vmcnt(0)
	v_pk_fma_f32 v[4:5], v[50:51], v[92:93], v[4:5] op_sel_hi:[1,0,1]
	v_fmac_f32_e32 v18, v59, v92
	s_cbranch_scc0 .LBB0_98
	s_barrier
	ds_write2st64_b32 v21, v4, v5 offset0:48 offset1:49
	ds_write_b32 v21, v18 offset:12800
	s_waitcnt lgkmcnt(0)
	s_barrier
	s_and_saveexec_b64 s[10:11], s[4:5]
	s_cbranch_execz .LBB0_41
	v_or_b32_e32 v2, s8, v9
	s_mul_i32 s8, s12, 0x1800
	v_add_u32_e32 v4, s8, v2
	v_readlane_b32 s36, v252, 2
	v_ashrrev_i32_e32 v5, 31, v4
	v_readlane_b32 s46, v252, 12
	v_readlane_b32 s47, v252, 13
	v_mad_u64_u32 v[40:41], s[8:9], s12, 3, v[8:9]
	s_nop 0
	v_lshl_add_u64 v[4:5], v[4:5], 2, s[46:47]
	global_load_dword v18, v[4:5], off
	ds_read2st64_b32 v[4:5], v22 offset0:48 offset1:51
	ds_read2st64_b32 v[34:35], v22 offset0:54 offset1:57
	ds_read2st64_b32 v[36:37], v22 offset0:60 offset1:63
	ds_read2st64_b32 v[38:39], v22 offset0:66 offset1:69
	v_mov_b64_e32 v[42:43], s[18:19]
	s_waitcnt lgkmcnt(3)
	v_add_f32_e32 v4, 0, v4
	v_add_f32_e32 v4, v4, v5
	s_waitcnt lgkmcnt(2)
	v_add_f32_e32 v4, v4, v34
	v_add_f32_e32 v4, v4, v35
	s_waitcnt lgkmcnt(1)
	v_add_f32_e32 v4, v4, v36
	v_add_f32_e32 v4, v4, v37
	s_waitcnt lgkmcnt(0)
	v_add_f32_e32 v4, v4, v38
	v_ashrrev_i32_e32 v3, 31, v2
	v_mad_i64_i32 v[40:41], s[8:9], v40, s53, v[42:43]
	v_add_f32_e32 v4, v4, v39
	v_lshl_add_u64 v[2:3], v[2:3], 2, v[40:41]
	v_readlane_b32 s37, v252, 3
	v_readlane_b32 s38, v252, 4
	v_readlane_b32 s39, v252, 5
	v_readlane_b32 s40, v252, 6
	v_readlane_b32 s41, v252, 7
	v_readlane_b32 s42, v252, 8
	v_readlane_b32 s43, v252, 9
	v_readlane_b32 s44, v252, 10
	v_readlane_b32 s45, v252, 11
	v_readlane_b32 s48, v252, 14
	v_readlane_b32 s49, v252, 15
	v_readlane_b32 s50, v252, 16
	v_readlane_b32 s51, v252, 17
	s_waitcnt vmcnt(0)
	v_add_f32_e32 v4, v4, v18
	global_store_dword v[2:3], v4, off
	s_branch .LBB0_41

.LBB0_164:
.LBB0_165:
	s_cmp_ge_i32 s60, s61
	s_cbranch_scc1 .LBB0_532
	s_lshr_b32 s0, s3, 16
	s_and_b32 s1, s3, 0xffff
	s_and_b32 s4, 0xffff, s68
	s_add_u32 s7, s26, 0xa1d0000
	s_addc_u32 s2, s27, 0
	s_add_u32 s76, s26, 0x164d0000
	v_writelane_b32 v252, s2, 50
	s_addc_u32 s77, s27, 0
	s_lshl_b32 s2, s84, 3
	v_writelane_b32 v252, s2, 51
	s_add_u32 s2, s26, 0x60d0000
	s_addc_u32 s3, s27, 0
	s_lshl_b32 s74, s62, 3
	s_add_u32 s8, s26, 0xa1d0800
	s_addc_u32 s9, s27, 0
	s_add_u32 s10, s26, 0xa1d1000
	s_mul_i32 s6, s1, s4
	s_mul_i32 s5, s63, s62
	s_addc_u32 s63, s27, 0
	s_bfe_i32 s6, s6, 0x180000
	s_mul_i32 s0, s6, s0
	s_add_i32 s0, s0, 63
	v_bfe_u32 v2, v0, 10, 10
	v_bfe_u32 v3, v0, 20, 10
	v_and_b32_e32 v168, 0x3ff, v0
	s_andn2_b32 s0, s0, 63
	v_mad_u32_u24 v0, v3, s1, v2
	s_cmp_lg_u32 s0, 64
	v_mad_u64_u32 v[0:1], s[0:1], v0, s4, v[168:169]
	s_cselect_b64 s[90:91], -1, 0
	s_add_u32 s0, s26, 0x5ec8000
	s_addc_u32 s1, s27, 0
	s_add_u32 s92, s26, 0x5e80000
	s_addc_u32 s93, s27, 0
	s_add_u32 s94, s26, 0x5ed0000
	s_addc_u32 s95, s27, 0
	s_add_u32 s68, s26, 0x1e6d0200
	s_addc_u32 s69, s27, 0
	s_add_u32 s70, s26, 0x1e6d0400
	v_writelane_b32 v252, s2, 52
	s_addc_u32 s71, s27, 0
	s_add_u32 s80, s26, 0x1e6d0500
	v_writelane_b32 v252, s3, 53
	v_writelane_b32 v252, s0, 54
	s_addc_u32 s81, s27, 0
	s_mov_b32 s75, 0x11000
	v_writelane_b32 v252, s1, 55
	s_add_u32 s0, s26, 0x1e6d0600
	s_addc_u32 s1, s27, 0
	v_writelane_b32 v252, s0, 56
	v_or3_b32 v2, v168, v2, v3
	s_mul_i32 s65, s5, s33
	v_writelane_b32 v252, s1, 57
	s_add_u32 s0, s26, 0x1e6d0700
	s_addc_u32 s1, s27, 0
	v_writelane_b32 v252, s0, 58
	v_mbcnt_lo_u32_b32 v3, -1, 0
	v_lshrrev_b32_e32 v1, 6, v0
	v_writelane_b32 v252, s1, 59
	s_add_u32 s0, s26, 0x1e6d0800
	s_addc_u32 s1, s27, 0
	v_writelane_b32 v252, s0, 60
	v_mbcnt_hi_u32_b32 v197, -1, v3
	v_mov_b32_e32 v171, 0
	v_writelane_b32 v252, s1, 61
	s_add_u32 s0, s26, 0x1e6d0900
	s_addc_u32 s1, s27, 0
	v_writelane_b32 v252, s0, 62
	v_mov_b32_e32 v169, 0x358637bd
	v_mov_b32_e32 v173, 1
	v_writelane_b32 v252, s1, 63
	s_add_u32 s0, s26, 0x1e6d0a00
	s_addc_u32 s1, s27, 0
	v_writelane_b32 v251, s0, 0
	v_readlane_b32 s44, v252, 2
	v_mov_b32_e32 v192, 0x100
	v_writelane_b32 v251, s1, 1
	s_add_u32 s0, s26, 0x1e6d0b00
	s_addc_u32 s1, s27, 0
	v_writelane_b32 v251, s0, 2
	v_mov_b32_e32 v193, 0x3ef1014c
	v_mov_b32_e32 v194, 0x3e4ccccd
	v_writelane_b32 v251, s1, 3
	s_add_u32 s0, s26, 0x1e6d0c00
	s_addc_u32 s1, s27, 0
	v_writelane_b32 v251, s0, 4
	v_mov_b32_e32 v195, 0x1800
	v_bfrev_b32_e32 v196, 1
	v_writelane_b32 v251, s1, 5
	s_add_u32 s0, s26, 0x1e6d0d00
	s_addc_u32 s1, s27, 0
	v_writelane_b32 v251, s0, 6
	v_or_b32_e32 v198, v197, v1
	v_mov_b32_e32 v199, 0x3e38aa3b
	v_writelane_b32 v251, s1, 7
	s_add_u32 s0, s26, 0x1e6d0e00
	s_addc_u32 s1, s27, 0
	v_writelane_b32 v251, s0, 8
	v_mov_b32_e32 v172, 0xbf3a00e3
	s_movk_i32 s79, 0x60
	v_writelane_b32 v251, s1, 9
	s_add_u32 s0, s26, 0x1e6d0f00
	s_addc_u32 s1, s27, 0
	v_writelane_b32 v251, s0, 10
	s_mov_b32 s85, 0x800000
	s_mov_b32 s33, 0x30000
	v_writelane_b32 v251, s1, 11
	s_add_u32 s0, s26, 0x1e6d1000
	s_addc_u32 s1, s27, 0
	v_writelane_b32 v251, s0, 12
	s_mov_b32 s99, 0x47800000
	s_mov_b32 s89, 0x4138aa3b
	v_writelane_b32 v251, s1, 13
	s_add_u32 s0, s26, 0x1e6d1100
	s_addc_u32 s1, s27, 0
	v_writelane_b32 v251, s0, 14
	s_mov_b64 s[96:97], 0x180
	s_mov_b32 s98, 0x3e6d3388
	v_writelane_b32 v251, s1, 15
	s_add_u32 s0, s26, 0x1e6d1200
	s_addc_u32 s1, s27, 0
	v_writelane_b32 v251, s0, 16
	s_mov_b32 s72, 0x3f07dc22
	s_mov_b32 s4, 0
	v_writelane_b32 v251, s1, 17
	s_add_u32 s0, s26, 0x1e6d1300
	s_addc_u32 s1, s27, 0
	v_writelane_b32 v251, s0, 18
	s_cmp_eq_u32 s64, 15
	v_readlane_b32 s45, v252, 3
	v_writelane_b32 v251, s1, 19
	s_cselect_b64 s[0:1], -1, 0
	v_writelane_b32 v251, s0, 20
	s_cmp_eq_u32 s64, 14
	v_readlane_b32 s48, v252, 6
	v_writelane_b32 v251, s1, 21
	s_cselect_b64 s[0:1], -1, 0
	v_writelane_b32 v251, s0, 22
	s_cmp_eq_u32 s64, 13
	v_readlane_b32 s49, v252, 7
	v_writelane_b32 v251, s1, 23
	s_cselect_b64 s[0:1], -1, 0
	v_writelane_b32 v251, s0, 24
	s_cmp_eq_u32 s64, 12
	v_readlane_b32 s56, v252, 14
	v_writelane_b32 v251, s1, 25
	s_cselect_b64 s[0:1], -1, 0
	v_writelane_b32 v251, s0, 26
	s_cmp_eq_u32 s64, 11
	v_readlane_b32 s57, v252, 15
	v_writelane_b32 v251, s1, 27
	s_cselect_b64 s[0:1], -1, 0
	v_writelane_b32 v251, s0, 28
	s_cmp_eq_u32 s64, 10
	v_readlane_b32 s58, v252, 16
	v_writelane_b32 v251, s1, 29
	s_cselect_b64 s[0:1], -1, 0
	v_writelane_b32 v251, s0, 30
	s_cmp_eq_u32 s64, 9
	v_readlane_b32 s59, v252, 17
	v_writelane_b32 v251, s1, 31
	s_cselect_b64 s[0:1], -1, 0
	v_writelane_b32 v251, s0, 32
	s_cmp_eq_u32 s64, 8
	s_mov_b32 s78, s7
	v_writelane_b32 v251, s1, 33
	s_cselect_b64 s[0:1], -1, 0
	v_writelane_b32 v251, s0, 34
	s_cmp_eq_u32 s64, 7
	s_mov_b32 s73, s10
	v_writelane_b32 v251, s1, 35
	s_cselect_b64 s[0:1], -1, 0
	v_writelane_b32 v251, s0, 36
	s_cmp_eq_u32 s64, 6
	v_readlane_b32 s46, v252, 4
	v_writelane_b32 v251, s1, 37
	s_cselect_b64 s[0:1], -1, 0
	v_writelane_b32 v251, s0, 38
	s_cmp_eq_u32 s64, 5
	v_readlane_b32 s47, v252, 5
	v_writelane_b32 v251, s1, 39
	s_cselect_b64 s[0:1], -1, 0
	v_writelane_b32 v251, s0, 40
	s_cmp_eq_u32 s64, 4
	v_readlane_b32 s50, v252, 8
	v_writelane_b32 v251, s1, 41
	s_cselect_b64 s[0:1], -1, 0
	v_writelane_b32 v251, s0, 42
	s_cmp_eq_u32 s64, 3
	v_readlane_b32 s51, v252, 9
	v_writelane_b32 v251, s1, 43
	s_cselect_b64 s[0:1], -1, 0
	v_writelane_b32 v251, s0, 44
	s_cmp_eq_u32 s64, 2
	v_readlane_b32 s52, v252, 10
	v_writelane_b32 v251, s1, 45
	s_cselect_b64 s[0:1], -1, 0
	v_writelane_b32 v251, s0, 46
	s_cmp_eq_u32 s64, 1
	v_readlane_b32 s53, v252, 11
	v_writelane_b32 v251, s1, 47
	s_cselect_b64 s[0:1], -1, 0
	v_writelane_b32 v251, s0, 48
	s_cmp_eq_u32 s64, 0
	v_readlane_b32 s54, v252, 12
	v_writelane_b32 v251, s1, 49
	s_cselect_b64 s[0:1], -1, 0
	v_writelane_b32 v251, s0, 50
	v_readlane_b32 s55, v252, 13
	s_nop 0
	v_writelane_b32 v251, s1, 51
	s_lshl_b32 s0, s64, 8
	s_add_u32 s0, s66, s0
	s_addc_u32 s1, s67, 0
	s_add_u32 s2, s0, 0x1400
	s_addc_u32 s3, s1, 0
	v_writelane_b32 v251, s2, 52
	s_add_u32 s0, s0, 0x2400
	s_addc_u32 s1, s1, 0
	v_writelane_b32 v251, s3, 53
	v_writelane_b32 v251, s0, 54
	s_movk_i32 s64, 0x1000
	s_mov_b64 s[66:67], 0x100
	v_writelane_b32 v251, s1, 55
	s_add_u32 s0, s26, 0x1e6d3400
	s_addc_u32 s1, s27, 0
	v_writelane_b32 v251, s0, 56
	s_nop 1
	v_writelane_b32 v251, s1, 57
	s_add_u32 s0, s26, 0x1e6d3500
	s_addc_u32 s1, s27, 0
	v_writelane_b32 v251, s0, 58
	s_nop 1
	v_writelane_b32 v251, s1, 59
	s_lshl_b32 s0, s84, 7
	s_lshl_b32 s1, s62, 7
	v_writelane_b32 v251, s1, 60
	s_or_b32 s1, s0, 3
	v_writelane_b32 v251, s1, 61
	s_or_b32 s1, s0, 2
	v_writelane_b32 v251, s1, 62
	v_writelane_b32 v251, s0, 63
	s_or_b32 s0, s0, 1
	v_writelane_b32 v250, s0, 0
	s_add_u32 s0, s26, 0x180
	v_writelane_b32 v250, s0, 1
	s_addc_u32 s0, s27, 0
	v_writelane_b32 v250, s0, 2
	s_mov_b32 s0, 0x11200
	s_addk_i32 s0, 0x100
	v_writelane_b32 v250, s0, 3
	s_mov_b32 s0, 0x20000
	s_addk_i32 s0, 0x100
	v_writelane_b32 v250, s0, 4
	s_mov_b32 s0, 0x20004
	s_addk_i32 s0, 0x100
	v_writelane_b32 v250, s0, 5
	s_lshl_b32 s0, s84, 5
	v_writelane_b32 v250, s0, 6
	s_lshl_b32 s0, s62, 5
	v_writelane_b32 v250, s0, 7
	s_add_i32 s0, s75, 0x100
	v_writelane_b32 v250, s0, 8
	v_cmp_lt_u32_e64 s[0:1], 63, v0
	s_nop 1
	v_writelane_b32 v250, s0, 9
	s_nop 1
	v_writelane_b32 v250, s1, 10
	v_cmp_eq_u32_e64 s[0:1], 0, v2
	s_nop 1
	v_writelane_b32 v250, s0, 11
	s_nop 1
	v_writelane_b32 v250, s1, 12
	v_cmp_eq_u32_e64 s[0:1], 0, v168
	s_nop 1
	v_writelane_b32 v250, s0, 13
	s_nop 1
	v_writelane_b32 v250, s1, 14
	v_writelane_b32 v250, s7, 15
	v_writelane_b32 v250, s76, 16
	s_nop 1
	v_writelane_b32 v250, s77, 17
	v_writelane_b32 v250, s74, 18
	v_writelane_b32 v250, s8, 19
	s_nop 1
	v_writelane_b32 v250, s9, 20
	v_writelane_b32 v250, s10, 21
	v_writelane_b32 v250, s65, 22
	v_writelane_b32 v250, s68, 23
	s_nop 1
	v_writelane_b32 v250, s69, 24
	v_writelane_b32 v250, s70, 25
	s_nop 1
	v_writelane_b32 v250, s71, 26
	v_writelane_b32 v250, s80, 27
	s_nop 1
	v_writelane_b32 v250, s81, 28
	v_writelane_b32 v250, s86, 29
	s_nop 1
	v_writelane_b32 v250, s87, 30
	v_writelane_b32 v250, s63, 31
	v_writelane_b32 v250, s90, 32
	s_nop 1
	v_writelane_b32 v250, s91, 33
	v_writelane_b32 v250, s92, 34
	s_nop 1
	v_writelane_b32 v250, s93, 35
	v_writelane_b32 v250, s94, 36
	v_writelane_b32 v250, s95, 37
	v_writelane_b32 v250, s84, 38
	s_branch .LBB0_171
	s_nop 0
	s_nop 0
	s_nop 0
	s_nop 0
	s_nop 0
	s_nop 0
	s_nop 0
	s_nop 0
	s_nop 0
	s_nop 0
	s_nop 0
	s_nop 0
	s_nop 0
	s_nop 0
	s_nop 0
	s_nop 0
	s_nop 0
	s_nop 0
	s_nop 0
	s_nop 0
	s_nop 0
